# attention tile loop: v_max3 row max, P*V value fragments read four MFMAs ahead; each tile iteration starts with s_sleep 9 so the 192 attention workgroups still finish just ahead of the scan flag at lo
# speedup vs baseline: 1.0052x; 1.0015x over previous
.LBB0_1113:
	s_sleep 9
	s_add_i32 s31, s68, 1
	s_cmp_lt_u32 s31, s11
	s_cselect_b64 s[60:61], -1, 0
	s_cmp_ge_u32 s31, s11
	s_cbranch_scc1 .LBB0_1115
	s_lshl_b64 s[70:71], s[0:1], 1
	v_lshl_add_u64 v[4:5], v[192:193], 0, s[70:71]
	global_load_dwordx4 v[114:117], v[196:197], off
	global_load_dwordx4 v[134:137], v[198:199], off
	v_lshl_add_u64 v[6:7], v[194:195], 0, s[70:71]
	global_load_dwordx4 v[138:141], v[4:5], off
	global_load_dwordx4 v[142:145], v[6:7], off

.LBB0_1118:
	s_nop 10
	v_max3_f32 v2, v82, v83, v84
	v_max3_f32 v4, v98, v99, v100
	v_max3_f32 v2, v2, v85, v86
	v_max3_f32 v4, v4, v101, v102
	v_max3_f32 v2, v2, v87, v88
	v_max3_f32 v4, v4, v103, v104
	v_max3_f32 v2, v2, v89, v90
	v_max3_f32 v4, v4, v105, v106
	v_max3_f32 v2, v2, v91, v92
	v_max3_f32 v4, v4, v107, v108
	v_max3_f32 v2, v2, v93, v94
	v_max3_f32 v4, v4, v109, v110
	v_max3_f32 v2, v2, v95, v96
	v_max3_f32 v4, v4, v111, v112
	v_max3_f32 v2, v2, v97, v113
	v_max_f32_e32 v2, v2, v4
	v_and_b32_e32 v5, 64, v157
	v_xor_b32_e32 v4, 32, v157
	v_add_u32_e32 v5, 64, v5
	v_cmp_lt_i32_e32 vcc, v4, v5
	s_nop 1
	v_cndmask_b32_e32 v4, v157, v4, vcc
	v_lshlrev_b32_e32 v4, 2, v4
	ds_bpermute_b32 v4, v4, v2
	s_waitcnt lgkmcnt(0)
	v_max3_f32 v4, v226, v2, v4
	v_sub_f32_e32 v2, v226, v4
	v_exp_f32_e32 v2, v2
	s_nop 0
	v_cmp_neq_f32_e32 vcc, 1.0, v2
	s_cbranch_vccz .LBB0_1120
	v_pk_mul_f32 v[80:81], v[2:3], v[80:81] op_sel_hi:[0,1]
	v_pk_mul_f32 v[78:79], v[2:3], v[78:79] op_sel_hi:[0,1]
	v_pk_mul_f32 v[76:77], v[2:3], v[76:77] op_sel_hi:[0,1]
	v_pk_mul_f32 v[74:75], v[2:3], v[74:75] op_sel_hi:[0,1]
	v_pk_mul_f32 v[72:73], v[2:3], v[72:73] op_sel_hi:[0,1]
	v_pk_mul_f32 v[70:71], v[2:3], v[70:71] op_sel_hi:[0,1]
	v_pk_mul_f32 v[68:69], v[2:3], v[68:69] op_sel_hi:[0,1]
	v_pk_mul_f32 v[66:67], v[2:3], v[66:67] op_sel_hi:[0,1]
	v_pk_mul_f32 v[64:65], v[2:3], v[64:65] op_sel_hi:[0,1]
	v_pk_mul_f32 v[62:63], v[2:3], v[62:63] op_sel_hi:[0,1]
	v_pk_mul_f32 v[60:61], v[2:3], v[60:61] op_sel_hi:[0,1]
	v_pk_mul_f32 v[58:59], v[2:3], v[58:59] op_sel_hi:[0,1]
	v_pk_mul_f32 v[56:57], v[2:3], v[56:57] op_sel_hi:[0,1]
	v_pk_mul_f32 v[54:55], v[2:3], v[54:55] op_sel_hi:[0,1]
	v_pk_mul_f32 v[52:53], v[2:3], v[52:53] op_sel_hi:[0,1]
	v_pk_mul_f32 v[50:51], v[2:3], v[50:51] op_sel_hi:[0,1]
	v_pk_mul_f32 v[48:49], v[2:3], v[48:49] op_sel_hi:[0,1]
	v_pk_mul_f32 v[46:47], v[2:3], v[46:47] op_sel_hi:[0,1]
	v_pk_mul_f32 v[44:45], v[2:3], v[44:45] op_sel_hi:[0,1]
	v_pk_mul_f32 v[42:43], v[2:3], v[42:43] op_sel_hi:[0,1]
	v_pk_mul_f32 v[40:41], v[2:3], v[40:41] op_sel_hi:[0,1]
	v_pk_mul_f32 v[38:39], v[2:3], v[38:39] op_sel_hi:[0,1]
	v_pk_mul_f32 v[36:37], v[2:3], v[36:37] op_sel_hi:[0,1]
	v_pk_mul_f32 v[34:35], v[2:3], v[34:35] op_sel_hi:[0,1]
	v_pk_mul_f32 v[32:33], v[2:3], v[32:33] op_sel_hi:[0,1]
	v_pk_mul_f32 v[30:31], v[2:3], v[30:31] op_sel_hi:[0,1]
	v_pk_mul_f32 v[28:29], v[2:3], v[28:29] op_sel_hi:[0,1]
	v_pk_mul_f32 v[26:27], v[2:3], v[26:27] op_sel_hi:[0,1]
	v_pk_mul_f32 v[24:25], v[2:3], v[24:25] op_sel_hi:[0,1]
	v_pk_mul_f32 v[22:23], v[2:3], v[22:23] op_sel_hi:[0,1]
	v_pk_mul_f32 v[20:21], v[2:3], v[20:21] op_sel_hi:[0,1]
	v_pk_mul_f32 v[18:19], v[2:3], v[18:19] op_sel_hi:[0,1]
.LBB0_1120:
	v_sub_f32_e32 v6, v82, v4
	v_sub_f32_e32 v5, v98, v4
	v_exp_f32_e32 v98, v6
	v_sub_f32_e32 v6, v99, v4
	v_exp_f32_e32 v99, v6
	v_sub_f32_e32 v6, v83, v4
	v_exp_f32_e32 v202, v6
	v_sub_f32_e32 v6, v100, v4
	v_exp_f32_e32 v100, v6
	v_sub_f32_e32 v6, v84, v4
	v_exp_f32_e32 v203, v6
	v_sub_f32_e32 v6, v101, v4
	v_exp_f32_e32 v101, v6
	v_sub_f32_e32 v6, v85, v4
	v_exp_f32_e32 v226, v6
	v_sub_f32_e32 v6, v102, v4
	v_exp_f32_e32 v102, v6
	v_sub_f32_e32 v6, v86, v4
	v_exp_f32_e32 v227, v6
	v_sub_f32_e32 v6, v103, v4
	v_exp_f32_e32 v103, v6
	v_sub_f32_e32 v6, v87, v4
	v_exp_f32_e32 v228, v6
	v_sub_f32_e32 v6, v104, v4
	v_exp_f32_e32 v104, v6
	v_sub_f32_e32 v6, v88, v4
	v_exp_f32_e32 v229, v6
	v_sub_f32_e32 v6, v105, v4
	v_exp_f32_e32 v105, v6
	v_sub_f32_e32 v6, v89, v4
	v_exp_f32_e32 v230, v6
	v_sub_f32_e32 v6, v106, v4
	v_exp_f32_e32 v106, v6
	v_sub_f32_e32 v6, v90, v4
	v_exp_f32_e32 v231, v6
	v_sub_f32_e32 v6, v107, v4
	v_exp_f32_e32 v107, v6
	v_sub_f32_e32 v6, v91, v4
	v_exp_f32_e32 v232, v6
	v_sub_f32_e32 v6, v108, v4
	v_exp_f32_e32 v108, v6
	v_sub_f32_e32 v6, v92, v4
	v_exp_f32_e32 v233, v6
	v_sub_f32_e32 v6, v109, v4
	v_exp_f32_e32 v109, v6
	v_sub_f32_e32 v6, v93, v4
	v_exp_f32_e32 v234, v6
	v_sub_f32_e32 v6, v110, v4
	v_exp_f32_e32 v110, v6
	v_sub_f32_e32 v6, v94, v4
	v_add3_u32 v235, s68, v171, v163
	v_exp_f32_e32 v94, v6
	v_sub_f32_e32 v6, v111, v4
	v_add_u32_e32 v86, 0x4000, v235
	v_exp_f32_e32 v111, v6
	ds_read2_b64 v[6:9], v86 offset0:128 offset1:130
	v_exp_f32_e32 v5, v5
	v_sub_f32_e32 v10, v112, v4
	v_sub_f32_e32 v87, v95, v4
	v_exp_f32_e32 v95, v10
	v_cvt_pk_bf16_f32 v10, v5, v99
	v_cvt_pk_bf16_f32 v11, v100, v101
	v_cvt_pk_bf16_f32 v12, v102, v103
	v_cvt_pk_bf16_f32 v13, v104, v105
	ds_read2_b64 v[14:17], v86 offset0:132 offset1:134
	ds_read2_b64 v[82:85], v86 offset0:136 offset1:138
	s_waitcnt lgkmcnt(2)
	v_mfma_f32_32x32x16_bf16 v[66:81], v[6:9], v[10:13], v[66:81]
	v_sub_f32_e32 v6, v113, v4
	v_exp_f32_e32 v112, v6
	v_cvt_pk_bf16_f32 v6, v106, v107
	v_cvt_pk_bf16_f32 v7, v108, v109
	v_cvt_pk_bf16_f32 v8, v110, v111
	v_cvt_pk_bf16_f32 v9, v95, v112
	v_exp_f32_e32 v113, v87
	ds_read2_b64 v[86:89], v86 offset0:140 offset1:142
	s_waitcnt lgkmcnt(2)
	v_mfma_f32_32x32x16_bf16 v[66:81], v[14:17], v[6:9], v[66:81]
	v_cvt_pk_bf16_f32 v14, v98, v202
	v_cvt_pk_bf16_f32 v15, v203, v226
	v_cvt_pk_bf16_f32 v16, v227, v228
	v_cvt_pk_bf16_f32 v17, v229, v230
	v_sub_f32_e32 v90, v96, v4
	v_exp_f32_e32 v96, v90
	v_add_u32_e32 v90, 0x5000, v235
	s_waitcnt lgkmcnt(1)
	v_mfma_f32_32x32x16_bf16 v[66:81], v[82:85], v[14:17], v[66:81]
	v_sub_f32_e32 v82, v97, v4
	v_exp_f32_e32 v97, v82
	v_cvt_pk_bf16_f32 v82, v231, v232
	v_cvt_pk_bf16_f32 v83, v233, v234
	v_cvt_pk_bf16_f32 v84, v94, v113
	v_cvt_pk_bf16_f32 v85, v96, v97
	v_add_f32_e32 v5, v5, v98
	v_add_f32_e32 v5, 0, v5
	v_add_u32_e32 v252, 0x5000, v235
	ds_read2_b64 v[236:239], v252 offset0:160 offset1:162
	ds_read2_b64 v[240:243], v252 offset0:164 offset1:166
	s_waitcnt lgkmcnt(2)
	v_mfma_f32_32x32x16_bf16 v[66:81], v[86:89], v[82:85], v[66:81]
	ds_read2_b64 v[244:247], v252 offset0:168 offset1:170
	ds_read2_b64 v[248:251], v252 offset0:172 offset1:174
	v_add_u32_e32 v253, 0x6000, v235
	v_add_f32_e32 v98, v99, v202
	v_add_f32_e32 v5, v5, v98
	v_add_f32_e32 v98, v100, v203
	v_add_f32_e32 v5, v5, v98
	s_waitcnt lgkmcnt(3)
	v_mfma_f32_32x32x16_bf16 v[50:65], v[236:239], v[10:13], v[50:65]
	ds_read2_b64 v[86:89], v253 offset0:192 offset1:194
	v_add_f32_e32 v98, v101, v226
	v_add_f32_e32 v5, v5, v98
	s_waitcnt lgkmcnt(3)
	v_mfma_f32_32x32x16_bf16 v[50:65], v[240:243], v[6:9], v[50:65]
	ds_read2_b64 v[90:93], v253 offset0:196 offset1:198
	v_add_f32_e32 v98, v102, v227
	v_add_f32_e32 v5, v5, v98
	s_waitcnt lgkmcnt(3)
	v_mfma_f32_32x32x16_bf16 v[50:65], v[244:247], v[14:17], v[50:65]
	ds_read2_b64 v[236:239], v253 offset0:200 offset1:202
	v_add_f32_e32 v98, v103, v228
	v_add_f32_e32 v5, v5, v98
	s_waitcnt lgkmcnt(3)
	v_mfma_f32_32x32x16_bf16 v[50:65], v[248:251], v[82:85], v[50:65]
	ds_read2_b64 v[240:243], v253 offset0:204 offset1:206
	v_add_u32_e32 v253, 0x7000, v235
	v_add_f32_e32 v98, v104, v229
	v_add_f32_e32 v5, v5, v98
	s_waitcnt lgkmcnt(3)
	v_mfma_f32_32x32x16_bf16 v[34:49], v[86:89], v[10:13], v[34:49]
	ds_read2_b64 v[244:247], v253 offset0:224 offset1:226
	v_add_f32_e32 v98, v105, v230
	v_add_f32_e32 v5, v5, v98
	s_waitcnt lgkmcnt(3)
	v_mfma_f32_32x32x16_bf16 v[34:49], v[90:93], v[6:9], v[34:49]
	ds_read2_b64 v[248:251], v253 offset0:228 offset1:230
	v_add_f32_e32 v98, v106, v231
	v_add_f32_e32 v5, v5, v98
	s_waitcnt lgkmcnt(3)
	v_mfma_f32_32x32x16_bf16 v[34:49], v[236:239], v[14:17], v[34:49]
	ds_read2_b64 v[86:89], v253 offset0:232 offset1:234
	v_add_f32_e32 v98, v107, v232
	v_add_f32_e32 v5, v5, v98
	s_waitcnt lgkmcnt(3)
	v_mfma_f32_32x32x16_bf16 v[34:49], v[240:243], v[82:85], v[34:49]
	ds_read2_b64 v[90:93], v253 offset0:236 offset1:238
	v_add_f32_e32 v98, v108, v233
	v_add_f32_e32 v5, v5, v98
	s_waitcnt lgkmcnt(3)
	v_mfma_f32_32x32x16_bf16 v[18:33], v[244:247], v[10:13], v[18:33]
	v_add_f32_e32 v98, v109, v234
	v_add_f32_e32 v5, v5, v98
	v_add_f32_e32 v98, v110, v94
	v_add_f32_e32 v5, v5, v98
	s_waitcnt lgkmcnt(2)
	v_mfma_f32_32x32x16_bf16 v[18:33], v[248:251], v[6:9], v[18:33]
	v_add_f32_e32 v98, v111, v113
	v_add_f32_e32 v5, v5, v98
	v_add_f32_e32 v98, v95, v96
	v_add_f32_e32 v5, v5, v98
	s_waitcnt lgkmcnt(1)
	v_mfma_f32_32x32x16_bf16 v[18:33], v[86:89], v[14:17], v[18:33]
	v_add_f32_e32 v98, v112, v97
	v_add_f32_e32 v5, v5, v98
	v_fmac_f32_e32 v5, v225, v2
	s_waitcnt lgkmcnt(0)
	v_mfma_f32_32x32x16_bf16 v[18:33], v[90:93], v[82:85], v[18:33]
	v_mov_b32_e32 v225, v5
	s_andn2_b64 vcc, exec, s[60:61]
	s_cbranch_vccz .LBB0_1122
	s_branch .LBB0_1123
